# token-mixing phase: one static s_setprio 1 for waves 4-7 (younger half) at phase entry, reset at exit
# baseline (speedup 1.0000x reference)
; #define LAS __attribute__((address_space(3)))
; __device__ __forceinline__ unsigned opq(unsigned x) { asm volatile("" : "+v"(x)); return x; }
; __device__ __forceinline__ void rwkv_chunk_item(const Frame& F, ArgsRef A, int l, int item, bool last) {
;     const int b = item >> 5, h = (item >> 1) & 15, dir = item & 1, tid = F.tid, lane = F.lane, w = F.wave, sgn = dir ? -1 : 1, l16 = lane & 15, g = lane >> 4;
;     LAS unsigned char* L = F.lds;
;     const bf16* ZR = RGN(bf16, R_ZR); const unsigned short* WLD = RGN(unsigned short, R_WDEC) + (size_t)dir * MT * 1024;   const bf16* AA = RGN(bf16, R_AA) + (size_t)dir * MT * 1024;
;     bf16* Y = RGN(bf16, R_Y) + (size_t)dir * MT * 1024;
;     const float* cw = AIN(12) + (size_t)l * 3 * RW_COLS;
;     const int j0 = 4 * l16, ch = h * 64 + j0;
;     const int tA = dir ? 2 : 0, tB = dir ? 0 : 2;
;     const f32x4 kkw = *(const f32x4*)(AIN(18) + l * 1024 + ch), kaw = *(const f32x4*)(AIN(19) + l * 1024 + ch);
;     const int cj = tid & 63, ct8 = tid >> 6;
;     const unsigned a_row = opq((unsigned)(((8 * w + g) * RC_LD + j0) * 2));
;     const unsigned a_tr = opq((unsigned)((((lane & 15) >> 2) * RC_LD + 4 * (lane & 3)) * 2));
;     const unsigned a_f8 = opq((unsigned)((l16 * RC_LD + 8 * g) * 2));
;     const unsigned a_f4 = opq((unsigned)((l16 * RC_LD + 4 * g) * 2));
;     f32x4 S[4];
; #pragma unroll
;     for (int t = 0; t < 4; ++t) S[t] = (f32x4){0.f, 0.f, 0.f, 0.f};
; __device__ __forceinline__ void phase_mix(const Frame& F, ArgsRef A, int l, bool last) {
;     unsigned long long tp = (MK_PROBE & 0x700) ? __builtin_amdgcn_s_memrealtime() : 0ull;
;     ...
;     for (int v = F.bid; v < 256; v += F.G) rwkv_chunk_item(F, A, l, ((v & 7) << 5) | (v >> 3), last);
.LBB0_760:
	s_or_b64 exec, exec, s[0:1]
	s_mov_b32 s2, s95
	s_mov_b32 s82, s93
	s_mov_b32 s10, s50
	s_mov_b32 s0, s92
	s_waitcnt lgkmcnt(0)
	s_barrier
	s_cmp_ge_u32 s95, 4
	s_cbranch_scc0 .Lp7_prio_done
	s_setprio 1
.Lp7_prio_done:
	v_mbcnt_lo_u32_b32 v163, -1, 0
	v_mbcnt_hi_u32_b32 v163, -1, v163
	s_cmp_eq_u32 s10, 1
	v_lshlrev_b32_e32 v0, 2, v163
	v_writelane_b32 v255, s0, 18
	s_mov_b64 s[76:77], s[90:91]
	s_mov_b64 s[0:1], s[88:89]
	s_mov_b64 s[8:9], s[86:87]
	s_cselect_b64 s[84:85], -1, 0
	s_cmpk_lt_i32 s82, 0x100
	v_lshlrev_b32_e32 v167, 3, v163
	v_and_b32_e32 v184, 12, v0
	s_cbranch_scc1 .LBB0_762
	s_ashr_i32 s97, s2, 1
	s_lshl_b32 s75, s2, 5
	v_lshlrev_b32_e32 v1, 3, v163
	v_and_b32_e32 v0, 12, v0
	v_mov_b32_e32 v203, 1
	v_lshl_add_u32 v165, s2, 6, v163
	s_cbranch_execz .LBB0_763
	s_branch .LBB0_823

; __device__ __forceinline__ void phase_mixout(const Frame& F, ArgsRef A, int l, int nrows) {
;     const int gw = F.bid * NWAVES + F.wave, NGW = F.G * NWAVES, lane = F.lane;
;     {
;         const bf16* ZR = RGN(bf16, R_ZR); const bf16* Y = RGN(bf16, R_Y); const bf16* G = RGN(bf16, R_G); bf16* ORW = RGN(bf16, R_ZA) + OC_RW; const float* BS = RGN(float, R_BS);
;         const float* cw = AIN(12) + (size_t)l * 3 * RW_COLS;
;         const int cg = F.wave & 3, c0 = cg * 256 + lane * 4, hd = cg * 4 + (lane >> 4);
;         f32x4 tpv[3];
; #pragma unroll
;         for (int tap = 0; tap < 3; ++tap) tpv[tap] = *(const f32x4*)(cw + tap * RW_COLS + 2 * 1024 + c0);
;         const f32x4 lnw = *(const f32x4*)(AIN(21) + l * 1024 + c0), lnb = *(const f32x4*)(AIN(22) + l * 1024 + c0);
;         for (int m = F.bid * 2 + (F.wave >> 2); m < nrows; m += 2 * F.G) {
;             int idx, len; if (m < ML) { idx = m & (SEQ - 1); len = SEQ; } else { idx = (m - ML) & (CL - 1); len = CL; }
;             const float fl = idx > 0 ? 1.f : 0.f, fr = idx < len - 1 ? 1.f : 0.f;
;             const bf16* z0 = ZR + (size_t)m * ZR_W + 2 * 1024 + c0; const bf16* zl = idx > 0 ? z0 - ZR_W : z0; const bf16* zrr = idx < len - 1 ? z0 + ZR_W : z0;
;             const v2u wc = *(const v2u*)z0, wl = *(const v2u*)zl, wr = *(const v2u*)zrr;
;             const f32x4 xc = (f32x4){bflo(wc.x), bfhi(wc.x), bflo(wc.y), bfhi(wc.y)}, xl = (f32x4){bflo(wl.x), bfhi(wl.x), bflo(wl.y), bfhi(wl.y)}, xr = (f32x4){bflo(wr.x), bfhi(wr.x), bflo(wr.y), bfhi(wr.y)};
;             const f32x4 v = xc * tpv[1] + xl * tpv[0] * fl + xr * tpv[2] * fr;
;             const v2u yw0 = *(const v2u*)(Y + (size_t)m * 1024 + c0), yw1 = *(const v2u*)(Y + ((size_t)MT + m) * 1024 + c0);
;             const f32x4 y0 = (f32x4){bflo(yw0.x), bfhi(yw0.x), bflo(yw0.y), bfhi(yw0.y)}, y1 = (f32x4){bflo(yw1.x), bfhi(yw1.x), bflo(yw1.y), bfhi(yw1.y)};
;             const float bs = BS[(size_t)m * 16 + hd] + BS[((size_t)MT + m) * 16 + hd];
.LBB0_904:
	s_or_b64 exec, exec, s[0:1]
	s_mov_b32 s16, s95
	s_mov_b32 s18, s50
	s_mov_b32 s26, s92
	s_mov_b32 s27, s93
	s_mov_b64 s[2:3], s[88:89]
	s_mov_b64 s[0:1], s[90:91]
	s_waitcnt lgkmcnt(0)
	s_barrier
	s_setprio 0
	v_mbcnt_lo_u32_b32 v3, -1, 0
	v_mbcnt_hi_u32_b32 v3, -1, v3
	s_cmp_eq_u32 s18, 1
	s_movk_i32 s2, 0x4800
	s_cselect_b32 s17, 0x4000, s2
	s_lshl_b32 s2, s27, 1
	s_ashr_i32 s3, s16, 2
	s_add_i32 s19, s2, s3
	s_mov_b64 s[4:5], s[86:87]
	s_cmp_ge_i32 s19, s17
	s_cbranch_scc1 .LBB0_907
	s_and_b32 s12, s16, 3
	s_load_dwordx4 s[8:11], s[4:5], 0xa8
	s_lshl_b32 s6, s12, 8
	v_lshl_add_u32 v0, v3, 2, s6
	s_lshl_b32 s6, s18, 10
	s_ashr_i32 s7, s6, 31
	s_lshl_b64 s[6:7], s[6:7], 2
	s_waitcnt lgkmcnt(0)
	s_add_u32 s8, s8, s6
	s_addc_u32 s9, s9, s7
	v_ashrrev_i32_e32 v1, 31, v0
	s_add_u32 s6, s10, s6
	v_lshlrev_b64 v[12:13], 2, v[0:1]
	s_addc_u32 s7, s11, s7
	v_lshl_add_u64 v[8:9], s[6:7], 0, v[12:13]
	s_load_dwordx2 s[6:7], s[4:5], 0x60
	v_lshl_add_u64 v[4:5], s[8:9], 0, v[12:13]
	s_mul_i32 s9, s18, 0xae00
	s_mul_hi_i32 s8, s18, 0xae00
	v_ashrrev_i32_e32 v14, 4, v3
	s_waitcnt lgkmcnt(0)
	s_add_u32 s6, s6, s9
	s_addc_u32 s7, s7, s8
	v_lshl_add_u64 v[20:21], s[6:7], 0, v[12:13]
	s_movk_i32 s6, 0x2000
	v_add_co_u32_e32 v12, vcc, s6, v20
	s_movk_i32 s6, 0x5000
	s_nop 0
	v_addc_co_u32_e32 v13, vcc, 0, v21, vcc
	v_add_co_u32_e32 v16, vcc, s6, v20
	global_load_dwordx4 v[4:7], v[4:5], off
	s_nop 0
	v_addc_co_u32_e32 v17, vcc, 0, v21, vcc
	v_add_co_u32_e32 v20, vcc, s38, v20
	global_load_dwordx4 v[8:11], v[8:9], off
	s_nop 0
	v_addc_co_u32_e32 v21, vcc, 0, v21, vcc
	v_lshl_add_u32 v24, s12, 2, v14
	global_load_dwordx4 v[12:15], v[12:13], off
	s_lshl_b32 s6, s26, 1
	global_load_dwordx4 v[16:19], v[16:17], off offset:2560
	s_ashr_i32 s7, s3, 31
	global_load_dwordx4 v[20:23], v[20:21], off offset:1024
	s_ashr_i32 s8, s2, 31
	s_add_u32 s2, s3, s2
	s_addc_u32 s3, s7, s8
	s_mul_i32 s7, s3, 0x2400
	s_mul_hi_u32 s8, s2, 0x2400
	s_add_i32 s7, s8, s7
	s_mul_i32 s8, s2, 0x2400
	s_add_u32 s8, s8, 0xbc00c00
	v_ashrrev_i32_e32 v25, 31, v24
	s_addc_u32 s9, s7, 0
	v_lshlrev_b64 v[28:29], 1, v[0:1]
	s_ashr_i32 s7, s6, 31
	s_lshl_b64 s[10:11], s[2:3], 6
	s_lshl_b64 s[12:13], s[2:3], 11
	v_lshl_add_u64 v[24:25], v[24:25], 2, s[10:11]
	s_lshl_b64 s[10:11], s[6:7], 6
	v_lshl_add_u64 v[26:27], s[12:13], 0, v[28:29]
	s_lshl_b64 s[12:13], s[6:7], 11
	s_mulk_i32 s3, 0x1e00
	s_mul_hi_u32 s7, s2, 0x1e00
	s_add_i32 s7, s7, s3
	s_mulk_i32 s2, 0x1e00
	s_add_u32 s2, s2, 0x15e01000
	s_addc_u32 s3, s7, 0
	v_lshl_add_u64 v[0:1], s[8:9], 0, v[28:29]
	s_mul_i32 s8, s26, 0x4800
	s_mul_hi_i32 s9, s6, 0x2400
	v_lshl_add_u64 v[28:29], s[2:3], 0, v[28:29]
	s_mul_i32 s14, s26, 0x3c00
	s_mul_hi_i32 s15, s6, 0x1e00
